# next-unit tile index by incremental update (pn+=4, carry pm+=8) for w_in and gate/up GEMMs instead of div/mod chain; dtype comment
# speedup vs baseline: 1.0071x; 1.0071x over previous
.LBB0_160:
	s_add_i32 s57, s57, 1
	s_mul_i32 s3, s57, s56
	s_mul_hi_u32 s27, s57, s9
	s_add_i32 s27, s27, s3
	s_mul_i32 s3, s57, s9
	s_add_u32 s30, s3, s11
	s_addc_u32 s31, s27, s33
	v_mov_b64_e32 v[0:1], 0x700
	v_cmp_lt_i64_e64 s[36:37], s[30:31], v[0:1]
	v_mov_b64_e32 v[0:1], 0x6ff
	v_cmp_gt_i64_e32 vcc, s[30:31], v[0:1]
	s_cbranch_vccnz .LBB0_162
	s_add_i32 s26, s2, 4
	s_cmp_gt_i32 s26, 6
	s_cselect_b32 s27, 7, 0
	s_cselect_b32 s28, 8, 0
	s_sub_i32 s26, s26, s27
	s_add_i32 s28, s38, s28

.LBB0_568:
	s_add_i32 s60, s60, 1
	s_mul_i32 s3, s60, s57
	s_mul_hi_u32 s27, s60, s9
	s_add_i32 s27, s27, s3
	s_mul_i32 s3, s60, s9
	s_add_u32 s30, s3, s11
	s_addc_u32 s31, s27, s33
	v_mov_b64_e32 v[0:1], 0x1600
	v_cmp_lt_i64_e64 s[36:37], s[30:31], v[0:1]
	v_mov_b64_e32 v[0:1], 0x15ff
	v_cmp_gt_i64_e32 vcc, s[30:31], v[0:1]
	s_cbranch_vccnz .LBB0_570
	s_add_i32 s26, s2, 4
	s_cmp_gt_i32 s26, 21
	s_cselect_b32 s27, 22, 0
	s_cselect_b32 s28, 8, 0
	s_sub_i32 s26, s26, s27
	s_add_i32 s28, s38, s28
